# attention unit order: C units weighted 2x in the cost merge (C units start earlier among the A units)
# speedup vs baseline: 1.0042x; 1.0042x over previous
; DI void prologue(const Args& a, LAS unsigned char* lds, int gw, int NGW, int wave, int lane) {
;     ...
;         while (ia < 128 || ic0 < 64 || ic1 < 64) {
;             const int t0 = 4 * (64 - ic0), t1 = 4 * (64 - ic1);
;             const int ca = ia < 128 ? 48 * (128 - ia) : -1, c0 = ic0 < 64 ? 24 * (t0 < nh[0] ? t0 : nh[0]) : -1, c1 = ic1 < 64 ? 24 * (t1 < nh[1] ? t1 : nh[1]) : -1;
;             if (ca >= c0 && ca >= c1) { const int qa = 127 - ia; tab[pos++] = (0u << 28) | ((unsigned)(q >> 2) << 24) | ((unsigned)(q & 3) << 16) | (unsigned)qa; ++ia; }
;             else if (c0 >= c1) { const int qc = 63 - ic0, bh = 2 * q; tab[pos++] = (2u << 28) | ((unsigned)(bh >> 3) << 24) | ((unsigned)(bh & 7) << 16) | (unsigned)qc; ++ic0; }
;             else { const int qc = 63 - ic1, bh = 2 * q + 1; tab[pos++] = (2u << 28) | ((unsigned)(bh >> 3) << 24) | ((unsigned)(bh & 7) << 16) | (unsigned)qc; ++ic1; }
;         }
.Lord_loop:
	v_add_u32_e32 v33, s8, v28
	v_mov_b32_e32 v34, v33
	v_lshlrev_b32_e32 v35, 2, v33
	v_sub_u32_e32 v34, 0x80, v34
	v_sub_u32_e32 v35, 0x100, v35
	v_min_i32_e32 v35, v35, v29
	v_cndmask_b32_e64 v34, v35, v34, s[4:5]
	v_cmp_gt_i32_e32 vcc, v10, v34
	v_cmp_gt_i32_e64 s[10:11], v11, v34
	v_cmp_ge_i32_e64 s[12:13], v10, v34
	v_sub_u32_e32 v35, 0x103, v34
	v_sub_u32_e32 v38, 0x100, v34
	v_lshrrev_b32_e32 v35, 2, v35
	v_lshrrev_b32_e32 v39, 2, v38
	v_sub_u32_e32 v38, 0x81, v34
	v_add_u32_e32 v39, 1, v39
	v_max_i32_e32 v38, 0, v38
	v_cndmask_b32_e32 v36, 0, v35, vcc
	v_cndmask_b32_e64 v37, 0, v35, s[10:11]
	v_cndmask_b32_e64 v39, 0, v39, s[12:13]
	v_cndmask_b32_e64 v36, v38, v36, s[4:5]
	v_cndmask_b32_e64 v37, v37, v39, s[6:7]
	v_add3_u32 v36, v33, v36, v37
	v_sub_u32_e32 v37, v31, v33
	v_lshlrev_b32_e32 v36, 2, v36
	v_or_b32_e32 v37, v37, v30
	v_add_co_u32_e32 v40, vcc, v6, v36
	s_nop 1
	v_addc_co_u32_e32 v41, vcc, 0, v7, vcc
	global_store_dword v[40:41], v37, off
	s_add_i32 s8, s8, 1
	s_cmp_lt_u32 s8, 64
	s_cbranch_scc1 .Lord_loop
